# m19: m15 with the L2-writeback skip at the weights-only seams (next-ph 2,8,10) made conditional on the verified XCD placement (fallback path validated separately)
# baseline (speedup 1.0000x reference)
; __device__ __forceinline__ unsigned xb_ld(unsigned* p)              { return __hip_atomic_load(p, __ATOMIC_RELAXED, __HIP_MEMORY_SCOPE_AGENT); }
; __device__ __forceinline__ unsigned xb_add(unsigned* p, unsigned v) { return __hip_atomic_fetch_add(p, v, __ATOMIC_RELAXED, __HIP_MEMORY_SCOPE_AGENT); }
; #define XB_SPIN(cond, bar) do { unsigned _sp = 0; while (cond) { __builtin_amdgcn_s_sleep(1); \
;     if ((++_sp & 255u) == 0u) { if (xb_ld(&(bar)[XB_TMO])) break; if (_sp > XB_SPIN_CAP) { atomicAdd(&(bar)[XB_TMO], 1u); break; } } } } while (0)
; __device__ __forceinline__ void xcd_barrier(const XcdBarrier& b) {
;     asm volatile("s_waitcnt vmcnt(0)" ::: "memory");
;     __syncthreads();
;     if (threadIdx.x == 0) {
;         unsigned* bar = b.bar;
;         __builtin_amdgcn_s_waitcnt(0);
;         unsigned nloc = b.st[0], nx = b.st[1];
;         if (nloc == 0u) { xcd_barrier_complete(bar, b.x, nloc, nx); b.st[0] = nloc; b.st[1] = nx; }
;         const unsigned old = xb_add(&bar[XB_XSUB(b.x)], 1u);
;         const unsigned gen = old / nloc;
;         if (old + 1u == (gen + 1u) * nloc) {
;             __builtin_amdgcn_fence(__ATOMIC_RELEASE, "agent");
;             asm volatile("s_waitcnt vmcnt(0)" ::: "memory");
;             const unsigned og = xb_add(&bar[XB_TOP], 1u);
;             const unsigned tg = og / nx;
;             if (og + 1u == (tg + 1u) * nx) xb_add(&bar[XB_TOPGEN], 1u);
;             else XB_SPIN(xb_ld(&bar[XB_TOPGEN]) == tg, bar);
;             __builtin_amdgcn_fence(__ATOMIC_ACQUIRE, "agent");
;             xb_add(&bar[XB_XGEN(b.x)], 1u);
;             asm volatile("s_waitcnt vmcnt(0)" ::: "memory");
;         } else {
;             XB_SPIN(xb_ld(&bar[XB_XGEN(b.x)]) == gen, bar);
;             __builtin_amdgcn_fence(__ATOMIC_ACQUIRE, "agent");
;             asm volatile("s_waitcnt vmcnt(0)" ::: "memory");
;         }
.LBB0_388:
	s_andn2_saveexec_b64 s[0:1], s[42:43]
	s_cbranch_execz .LBB0_10
	s_mov_b64 s[42:43], exec
	s_lshl_b32 s0, 1, s76
	s_and_b32 s0, s0, 0xe7cc
	s_cbranch_scc0 .Lgb_global
	v_readlane_b32 s0, v254, 38
	s_nop 1
	v_mov_b32_e32 v18, s0
	ds_read_b32 v19, v18 offset:8
	s_waitcnt lgkmcnt(0)
	v_readfirstlane_b32 s0, v19
	s_cmp_eq_u32 s0, 1
	s_cbranch_scc1 .Lgb_local_ok
	s_cmp_eq_u32 s0, 2
	s_cbranch_scc1 .Lgb_global
	v_readlane_b32 s0, v254, 62
	v_readlane_b32 s1, v254, 63
	s_nop 1
	s_load_dwordx2 s[44:45], s[0:1], 0xa0
	s_waitcnt lgkmcnt(0)
	s_add_u32 s44, s44, 0xda04000
	s_addc_u32 s45, s45, 0
	v_mov_b32_e32 v20, 0
	global_load_dword v21, v20, s[44:45] sc1
	global_load_dword v22, v20, s[44:45] offset:256 sc1
	global_load_dword v23, v20, s[44:45] offset:512 sc1
	global_load_dword v24, v20, s[44:45] offset:768 sc1
	global_load_dword v25, v20, s[44:45] offset:1024 sc1
	global_load_dword v26, v20, s[44:45] offset:1280 sc1
	global_load_dword v27, v20, s[44:45] offset:1536 sc1
	global_load_dword v28, v20, s[44:45] offset:1792 sc1
	s_waitcnt vmcnt(0)
	v_add_u32_e32 v29, -1, v21
	v_and_b32_e32 v29, v29, v21
	v_mov_b32_e32 v30, v21
	v_add_u32_e32 v31, -1, v22
	v_and_b32_e32 v31, v31, v22
	v_or_b32_e32 v29, v29, v31
	v_min_u32_e32 v30, v30, v22
	v_add_u32_e32 v31, -1, v23
	v_and_b32_e32 v31, v31, v23
	v_or_b32_e32 v29, v29, v31
	v_min_u32_e32 v30, v30, v23
	v_add_u32_e32 v31, -1, v24
	v_and_b32_e32 v31, v31, v24
	v_or_b32_e32 v29, v29, v31
	v_min_u32_e32 v30, v30, v24
	v_add_u32_e32 v31, -1, v25
	v_and_b32_e32 v31, v31, v25
	v_or_b32_e32 v29, v29, v31
	v_min_u32_e32 v30, v30, v25
	v_add_u32_e32 v31, -1, v26
	v_and_b32_e32 v31, v31, v26
	v_or_b32_e32 v29, v29, v31
	v_min_u32_e32 v30, v30, v26
	v_add_u32_e32 v31, -1, v27
	v_and_b32_e32 v31, v31, v27
	v_or_b32_e32 v29, v29, v31
	v_min_u32_e32 v30, v30, v27
	v_add_u32_e32 v31, -1, v28
	v_and_b32_e32 v31, v31, v28
	v_or_b32_e32 v29, v29, v31
	v_min_u32_e32 v30, v30, v28
	v_cmp_eq_u32_e32 vcc, 0, v29
	v_cmp_ne_u32_e64 s[0:1], 0, v30
	s_nop 1
	s_and_b64 s[0:1], s[0:1], vcc
	s_and_b64 s[0:1], s[0:1], exec
	s_cselect_b32 s0, 1, 2
	v_mov_b32_e32 v19, s0
	ds_write_b32 v18, v19 offset:8
	s_waitcnt lgkmcnt(0)
	s_cmp_eq_u32 s0, 1
	s_cbranch_scc1 .Lgb_local_ok
	s_branch .Lgb_global
.Lgb_local_ok:
	s_lshl_b32 s0, 1, s76
	s_and_b32 s0, s0, 0x504
	s_cbranch_scc1 .Lgb_nowb
	s_branch .LBB0_405
.Lgb_global:
	s_lshl_b32 s0, 1, s76
	s_and_b32 s0, s0, 0x2
	s_cbranch_scc1 .Lgb_nowb
	buffer_wbl2 sc1
